# diff fast block: each step's first MFMA issued directly behind the barrier (2-5 scalar bookkeeping instructions moved behind it)
# speedup vs baseline: 1.0010x; 1.0010x over previous
.Ldf_fast:
	s_add_i32 s0, s43, 2
	s_waitcnt vmcnt(4) lgkmcnt(0)
	s_barrier
	v_mfma_f32_32x32x16_bf16 v[2:17], v[158:161], v[182:185], v[2:17]
	s_add_i32 s20, s58, s43
	s_cmp_lt_i32 s20, s89
	v_subrev_u32_e32 v198, 64, v197
	s_cselect_b64 s[26:27], -1, 0
	v_cvt_f32_i32_e32 v98, v198
	v_cndmask_b32_e64 v188, -v193, v193, s[26:27]
	v_add_u32_e32 v199, s15, v240
	ds_read_b64_tr_b16 v[200:201], v199 offset:51200
	ds_read_b64_tr_b16 v[202:203], v199 offset:51712
	v_fma_f32 v114, v188, v98, -v233
	v_exp_f32_e32 v66, v66
	v_exp_f32_e32 v67, v67
	v_fmamk_f32 v98, v188, 0x42000000, v114
	v_add_f32_e32 v115, v188, v114
	v_mfma_f32_32x32x16_bf16 v[2:17], v[154:157], v[178:181], v[2:17]
	ds_read_b64_tr_b16 v[182:183], v199 offset:52224
	ds_read_b64_tr_b16 v[184:185], v199 offset:52736
	v_fmamk_f32 v99, v188, 0x42040000, v114
	v_fma_f32 v116, 2.0, v188, v114
	v_exp_f32_e32 v68, v68
	v_exp_f32_e32 v69, v69
	s_waitcnt lgkmcnt(2)
	v_mfma_f32_32x32x16_bf16 v[2:17], v[150:153], v[200:203], v[2:17]
	ds_read_b64_tr_b16 v[178:179], v199 offset:53248
	ds_read_b64_tr_b16 v[180:181], v199 offset:53760
	v_add_f32_e32 v187, v187, v66
	v_fmamk_f32 v100, v188, 0x42080000, v114
	v_fmamk_f32 v117, v188, 0x40400000, v114
	v_cvt_pk_bf16_f32 v174, v66, v67
	v_add_f32_e32 v187, v67, v187
	v_exp_f32_e32 v70, v70
	s_waitcnt lgkmcnt(2)
	v_mfma_f32_32x32x16_bf16 v[2:17], v[146:149], v[182:185], v[2:17]
	ds_read_b64_tr_b16 v[200:201], v199 offset:54272
	ds_read_b64_tr_b16 v[202:203], v199 offset:54784
	v_fma_f32 v101, v188, s16, v114
	v_fma_f32 v102, v188, s17, v114
	v_fmamk_f32 v118, v188, 0x41000000, v114
	v_exp_f32_e32 v71, v71
	v_add_f32_e32 v187, v187, v68
	s_waitcnt lgkmcnt(2)
	v_mfma_f32_32x32x16_bf16 v[18:33], v[158:161], v[178:181], v[18:33]
	ds_read_b64_tr_b16 v[182:183], v199 offset:55296
	ds_read_b64_tr_b16 v[184:185], v199 offset:55808
	v_fmamk_f32 v119, v188, 0x41100000, v114
	v_fmamk_f32 v103, v188, 0x42240000, v114
	v_cvt_pk_bf16_f32 v175, v68, v69
	v_add_f32_e32 v187, v187, v69
	v_exp_f32_e32 v72, v72
	s_waitcnt lgkmcnt(2)
	v_mfma_f32_32x32x16_bf16 v[18:33], v[154:157], v[200:203], v[18:33]
	ds_read_b64_tr_b16 v[178:179], v199 offset:56320
	ds_read_b64_tr_b16 v[180:181], v199 offset:56832
	v_fmamk_f32 v120, v188, 0x41200000, v114
	v_fmamk_f32 v104, v188, 0x42280000, v114
	v_exp_f32_e32 v73, v73
	v_add_f32_e32 v187, v187, v70
	v_cvt_pk_bf16_f32 v176, v70, v71
	s_waitcnt lgkmcnt(2)
	v_mfma_f32_32x32x16_bf16 v[18:33], v[150:153], v[182:185], v[18:33]
	ds_read_b64_tr_b16 v[200:201], v199 offset:57344
	ds_read_b64_tr_b16 v[202:203], v199 offset:57856
	v_fmamk_f32 v121, v188, 0x41300000, v114
	v_fmamk_f32 v105, v188, 0x422c0000, v114
	v_add_f32_e32 v182, v187, v71
	v_exp_f32_e32 v74, v74
	v_exp_f32_e32 v75, v75
	s_waitcnt lgkmcnt(2)
	v_mfma_f32_32x32x16_bf16 v[18:33], v[146:149], v[178:181], v[18:33]
	ds_read_b64_tr_b16 v[204:205], v199 offset:58368
	ds_read_b64_tr_b16 v[206:207], v199 offset:58880
	v_add_f32_e32 v178, v182, v72
	v_fmamk_f32 v106, v188, 0x42400000, v114
	v_fma_f32 v122, v188, s48, v114
	v_fma_f32 v123, v188, s49, v114
	v_cvt_pk_bf16_f32 v177, v72, v73
	v_add_f32_e32 v187, v73, v178
	s_waitcnt lgkmcnt(2)
	v_mfma_f32_32x32x16_bf16 v[34:49], v[158:161], v[200:203], v[34:49]
	ds_read_b64_tr_b16 v[182:183], v199 offset:59392
	ds_read_b64_tr_b16 v[184:185], v199 offset:59904
	v_fmamk_f32 v107, v188, 0x42440000, v114
	v_fmamk_f32 v124, v188, 0x41900000, v114
	v_exp_f32_e32 v76, v76
	v_exp_f32_e32 v77, v77
	s_waitcnt lgkmcnt(2)
	v_mfma_f32_32x32x16_bf16 v[34:49], v[154:157], v[204:207], v[34:49]
	ds_read_b64_tr_b16 v[178:179], v199 offset:60416
	ds_read_b64_tr_b16 v[180:181], v199 offset:60928
	v_add_f32_e32 v187, v187, v74
	v_fmamk_f32 v108, v188, 0x42480000, v114
	v_fmamk_f32 v125, v188, 0x41980000, v114
	v_cvt_pk_bf16_f32 v170, v74, v75
	v_add_f32_e32 v200, v75, v187
	v_exp_f32_e32 v78, v78
	s_add_u32 s6, s76, s62
	s_addc_u32 s7, s77, s63
	s_add_u32 s26, s6, 0x30000
	s_addc_u32 s27, s7, 0
	s_add_u32 s6, s78, s62
	s_addc_u32 s7, s79, s63
	s_add_u32 s70, s6, 0x30000
	s_addc_u32 s71, s7, 0
	s_add_i32 s6, 0, s59
	s_add_i32 s7, s81, s90
	s_add_u32 s84, s26, 0x8000
	s_addc_u32 s85, s27, 0
	s_add_i32 s15, s6, 0x2000
	s_mov_b32 m0, s6
	s_nop 0
	global_load_lds_dwordx4 v191, s[26:27]
	s_mov_b32 m0, s15
	s_nop 0
	global_load_lds_dwordx4 v191, s[84:85]
	s_mov_b32 m0, s21
	s_add_u32 s26, s70, 0x80
	s_addc_u32 s27, s71, 0
	s_add_i32 s6, s7, 0x2000
	s_mov_b32 m0, s7
	s_nop 0
	global_load_lds_dwordx4 v192, s[70:71]
	s_mov_b32 m0, s6
	s_nop 0
	global_load_lds_dwordx4 v192, s[26:27]
	s_mov_b32 m0, s15
	s_waitcnt lgkmcnt(2)
	v_mfma_f32_32x32x16_bf16 v[34:49], v[150:153], v[182:185], v[34:49]
	ds_read_b64_tr_b16 v[202:203], v199 offset:61440
	ds_read_b64_tr_b16 v[204:205], v199 offset:61952
	v_fma_f32 v109, v188, s56, v114
	v_fma_f32 v110, v188, s57, v114
	v_fmamk_f32 v126, v188, 0x41c00000, v114
	v_exp_f32_e32 v79, v79
	v_add_f32_e32 v187, v200, v76
	s_waitcnt lgkmcnt(2)
	v_mfma_f32_32x32x16_bf16 v[34:49], v[146:149], v[178:181], v[34:49]
	ds_read_b64_tr_b16 v[182:183], v199 offset:62464
	ds_read_b64_tr_b16 v[184:185], v199 offset:62976
	v_fmamk_f32 v127, v188, 0x41c80000, v114
	v_fmamk_f32 v111, v188, 0x42640000, v114
	v_cvt_pk_bf16_f32 v171, v76, v77
	v_add_f32_e32 v187, v187, v77
	v_exp_f32_e32 v80, v80
	s_waitcnt lgkmcnt(2)
	v_mfma_f32_32x32x16_bf16 v[50:65], v[158:161], v[202:205], v[50:65]
	ds_read_b64_tr_b16 v[178:179], v199 offset:63488
	ds_read_b64_tr_b16 v[180:181], v199 offset:64000
	v_fmamk_f32 v128, v188, 0x41d00000, v114
	v_fmamk_f32 v112, v188, 0x42680000, v114
	v_exp_f32_e32 v81, v81
	v_add_f32_e32 v187, v187, v78
	v_cvt_pk_bf16_f32 v172, v78, v79
	s_waitcnt lgkmcnt(2)
	v_mfma_f32_32x32x16_bf16 v[50:65], v[154:157], v[182:185], v[50:65]
	ds_read_b64_tr_b16 v[200:201], v199 offset:64512
	ds_read_b64_tr_b16 v[202:203], v199 offset:65024
	v_fmamk_f32 v129, v188, 0x41d80000, v114
	v_fmamk_f32 v113, v188, 0x426c0000, v114
	v_exp_f32_e32 v82, v82
	v_exp_f32_e32 v83, v83
	v_add_f32_e32 v186, v187, v79
	s_waitcnt lgkmcnt(2)
	v_mfma_f32_32x32x16_bf16 v[50:65], v[150:153], v[178:181], v[50:65]
	ds_read_b128 v[182:185], v190 offset:16384
	v_add_f32_e32 v178, v186, v80
	v_cvt_pk_bf16_f32 v173, v80, v81
	v_add_f32_e32 v186, v81, v178
	v_exp_f32_e32 v84, v84
	v_exp_f32_e32 v85, v85
	s_waitcnt lgkmcnt(1)
	v_mfma_f32_32x32x16_bf16 v[50:65], v[146:149], v[200:203], v[50:65]
	ds_read_b128 v[178:181], v190 offset:24576
	v_add_f32_e32 v186, v186, v82
	v_cvt_pk_bf16_f32 v166, v82, v83
	v_add_f32_e32 v199, v83, v186
	v_exp_f32_e32 v86, v86
	v_exp_f32_e32 v87, v87
	s_waitcnt lgkmcnt(1)
	v_mfma_f32_32x32x16_bf16 v[114:129], v[182:185], v[130:133], v[114:129]
	ds_read_b128 v[186:189], v194 offset:16384
	v_add_f32_e32 v182, v199, v84
	v_cvt_pk_bf16_f32 v167, v84, v85
	v_add_f32_e32 v199, v85, v182
	v_exp_f32_e32 v88, v88
	v_exp_f32_e32 v89, v89
	s_waitcnt lgkmcnt(1)
	v_mfma_f32_32x32x16_bf16 v[98:113], v[178:181], v[130:133], v[98:113]
	ds_read_b128 v[182:185], v194 offset:24576
	v_add_f32_e32 v178, v199, v86
	v_cvt_pk_bf16_f32 v168, v86, v87
	v_add_f32_e32 v199, v87, v178
	v_exp_f32_e32 v90, v90
	v_exp_f32_e32 v91, v91
	s_waitcnt lgkmcnt(1)
	v_mfma_f32_32x32x16_bf16 v[114:129], v[186:189], v[134:137], v[114:129]
	ds_read_b128 v[178:181], v195 offset:16384
	v_add_f32_e32 v186, v199, v88
	v_cvt_pk_bf16_f32 v169, v88, v89
	v_add_f32_e32 v199, v89, v186
	v_exp_f32_e32 v92, v92
	v_exp_f32_e32 v93, v93
	s_waitcnt lgkmcnt(1)
	v_mfma_f32_32x32x16_bf16 v[98:113], v[182:185], v[134:137], v[98:113]
	ds_read_b128 v[186:189], v195 offset:24576
	v_add_f32_e32 v182, v199, v90
	v_cvt_pk_bf16_f32 v162, v90, v91
	v_add_f32_e32 v182, v91, v182
	v_exp_f32_e32 v94, v94
	v_exp_f32_e32 v95, v95
	s_waitcnt lgkmcnt(1)
	v_mfma_f32_32x32x16_bf16 v[114:129], v[178:181], v[138:141], v[114:129]
	ds_read_b128 v[200:203], v196 offset:16384
	v_add_f32_e32 v178, v182, v92
	v_cvt_pk_bf16_f32 v163, v92, v93
	v_add_f32_e32 v178, v93, v178
	v_exp_f32_e32 v96, v96
	v_exp_f32_e32 v97, v97
	s_waitcnt lgkmcnt(1)
	v_mfma_f32_32x32x16_bf16 v[98:113], v[186:189], v[138:141], v[98:113]
	ds_read_b128 v[204:207], v196 offset:24576
	v_add_f32_e32 v165, v178, v94
	v_add_f32_e32 v165, v95, v165
	v_add_f32_e32 v178, v96, v165
	v_cvt_pk_bf16_f32 v164, v94, v95
	v_cvt_pk_bf16_f32 v165, v96, v97
	v_add_f32_e32 v187, v97, v178
	s_waitcnt lgkmcnt(1)
	v_mfma_f32_32x32x16_bf16 v[114:129], v[200:203], v[142:145], v[114:129]
	v_add_u32_e32 v199, s80, v240
	ds_read_b64_tr_b16 v[182:183], v199 offset:49152
	ds_read_b64_tr_b16 v[184:185], v199 offset:49664
	s_waitcnt lgkmcnt(2)
	v_mfma_f32_32x32x16_bf16 v[98:113], v[204:207], v[142:145], v[98:113]
	ds_read_b64_tr_b16 v[178:179], v199 offset:50176
	ds_read_b64_tr_b16 v[180:181], v199 offset:50688
	s_waitcnt vmcnt(4) lgkmcnt(0)
	s_barrier
	v_mfma_f32_32x32x16_bf16 v[2:17], v[174:177], v[182:185], v[2:17]
	s_add_i32 s6, s81, 0x4000
	s_cmp_lg_u32 s81, 0x10000
	s_cselect_b32 s21, s6, 0
	s_add_i32 s20, s20, 1
	s_cmp_lt_i32 s20, s89
	s_cselect_b64 s[6:7], -1, 0
	v_cvt_f32_i32_e32 v66, v197
	v_cndmask_b32_e64 v188, -v193, v193, s[6:7]
	ds_read_b64_tr_b16 v[200:201], v199 offset:51200
	ds_read_b64_tr_b16 v[202:203], v199 offset:51712
	v_fma_f32 v66, v188, v66, -v233
	v_exp_f32_e32 v114, v114
	v_exp_f32_e32 v115, v115
	v_fmamk_f32 v82, v188, 0x42000000, v66
	v_add_f32_e32 v67, v188, v66
	v_mfma_f32_32x32x16_bf16 v[2:17], v[170:173], v[178:181], v[2:17]
	ds_read_b64_tr_b16 v[182:183], v199 offset:52224
	ds_read_b64_tr_b16 v[184:185], v199 offset:52736
	v_fmamk_f32 v83, v188, 0x42040000, v66
	v_fma_f32 v68, 2.0, v188, v66
	v_exp_f32_e32 v116, v116
	v_exp_f32_e32 v117, v117
	s_waitcnt lgkmcnt(2)
	v_mfma_f32_32x32x16_bf16 v[2:17], v[166:169], v[200:203], v[2:17]
	ds_read_b64_tr_b16 v[178:179], v199 offset:53248
	ds_read_b64_tr_b16 v[180:181], v199 offset:53760
	v_add_f32_e32 v187, v187, v114
	v_fmamk_f32 v84, v188, 0x42080000, v66
	v_fmamk_f32 v69, v188, 0x40400000, v66
	v_cvt_pk_bf16_f32 v158, v114, v115
	v_add_f32_e32 v187, v115, v187
	v_exp_f32_e32 v118, v118
	s_waitcnt lgkmcnt(2)
	v_mfma_f32_32x32x16_bf16 v[2:17], v[162:165], v[182:185], v[2:17]
	ds_read_b64_tr_b16 v[200:201], v199 offset:54272
	ds_read_b64_tr_b16 v[202:203], v199 offset:54784
	v_fma_f32 v85, v188, s16, v66
	v_fma_f32 v86, v188, s17, v66
	v_fmamk_f32 v70, v188, 0x41000000, v66
	v_exp_f32_e32 v119, v119
	v_add_f32_e32 v187, v187, v116
	s_waitcnt lgkmcnt(2)
	v_mfma_f32_32x32x16_bf16 v[18:33], v[174:177], v[178:181], v[18:33]
	ds_read_b64_tr_b16 v[182:183], v199 offset:55296
	ds_read_b64_tr_b16 v[184:185], v199 offset:55808
	v_fmamk_f32 v71, v188, 0x41100000, v66
	v_fmamk_f32 v87, v188, 0x42240000, v66
	v_cvt_pk_bf16_f32 v159, v116, v117
	v_add_f32_e32 v187, v187, v117
	v_exp_f32_e32 v120, v120
	s_waitcnt lgkmcnt(2)
	v_mfma_f32_32x32x16_bf16 v[18:33], v[170:173], v[200:203], v[18:33]
	ds_read_b64_tr_b16 v[178:179], v199 offset:56320
	ds_read_b64_tr_b16 v[180:181], v199 offset:56832
	v_fmamk_f32 v72, v188, 0x41200000, v66
	v_fmamk_f32 v88, v188, 0x42280000, v66
	v_exp_f32_e32 v121, v121
	v_add_f32_e32 v187, v187, v118
	v_cvt_pk_bf16_f32 v160, v118, v119
	s_waitcnt lgkmcnt(2)
	v_mfma_f32_32x32x16_bf16 v[18:33], v[166:169], v[182:185], v[18:33]
	ds_read_b64_tr_b16 v[200:201], v199 offset:57344
	ds_read_b64_tr_b16 v[202:203], v199 offset:57856
	v_fmamk_f32 v73, v188, 0x41300000, v66
	v_fmamk_f32 v89, v188, 0x422c0000, v66
	v_add_f32_e32 v182, v187, v119
	v_exp_f32_e32 v122, v122
	v_exp_f32_e32 v123, v123
	s_waitcnt lgkmcnt(2)
	v_mfma_f32_32x32x16_bf16 v[18:33], v[162:165], v[178:181], v[18:33]
	ds_read_b64_tr_b16 v[204:205], v199 offset:58368
	ds_read_b64_tr_b16 v[206:207], v199 offset:58880
	v_add_f32_e32 v178, v182, v120
	v_fmamk_f32 v90, v188, 0x42400000, v66
	v_fma_f32 v74, v188, s48, v66
	v_fma_f32 v75, v188, s49, v66
	v_cvt_pk_bf16_f32 v161, v120, v121
	v_add_f32_e32 v187, v121, v178
	s_waitcnt lgkmcnt(2)
	v_mfma_f32_32x32x16_bf16 v[34:49], v[174:177], v[200:203], v[34:49]
	ds_read_b64_tr_b16 v[182:183], v199 offset:59392
	ds_read_b64_tr_b16 v[184:185], v199 offset:59904
	v_fmamk_f32 v91, v188, 0x42440000, v66
	v_fmamk_f32 v76, v188, 0x41900000, v66
	v_exp_f32_e32 v124, v124
	v_exp_f32_e32 v125, v125
	s_waitcnt lgkmcnt(2)
	v_mfma_f32_32x32x16_bf16 v[34:49], v[170:173], v[204:207], v[34:49]
	ds_read_b64_tr_b16 v[178:179], v199 offset:60416
	ds_read_b64_tr_b16 v[180:181], v199 offset:60928
	v_add_f32_e32 v187, v187, v122
	v_fmamk_f32 v92, v188, 0x42480000, v66
	v_fmamk_f32 v77, v188, 0x41980000, v66
	v_cvt_pk_bf16_f32 v154, v122, v123
	v_add_f32_e32 v198, v123, v187
	v_exp_f32_e32 v126, v126
	s_add_u32 s6, s76, s62
	s_addc_u32 s7, s77, s63
	s_add_u32 s6, s6, 0x40000
	s_addc_u32 s7, s7, 0
	s_add_u32 s15, s78, s62
	s_addc_u32 s20, s79, s63
	s_add_u32 s24, s15, 0x40000
	s_addc_u32 s25, s20, 0
	s_add_i32 s15, 0x4000, s59
	s_add_i32 s20, s21, s90
	s_add_u32 s26, s6, 0x8000
	s_addc_u32 s27, s7, 0
	s_add_i32 s68, s15, 0x2000
	s_mov_b32 m0, s15
	s_nop 0
	global_load_lds_dwordx4 v191, s[6:7]
	s_mov_b32 m0, s68
	s_nop 0
	global_load_lds_dwordx4 v191, s[26:27]
	s_mov_b32 m0, s69
	s_add_u32 s6, s24, 0x80
	s_addc_u32 s7, s25, 0
	s_add_i32 s15, s20, 0x2000
	s_mov_b32 m0, s20
	s_nop 0
	global_load_lds_dwordx4 v192, s[24:25]
	s_mov_b32 m0, s15
	s_nop 0
	global_load_lds_dwordx4 v192, s[6:7]
	s_mov_b32 m0, s26
	s_waitcnt lgkmcnt(2)
	v_mfma_f32_32x32x16_bf16 v[34:49], v[166:169], v[182:185], v[34:49]
	ds_read_b64_tr_b16 v[200:201], v199 offset:61440
	ds_read_b64_tr_b16 v[202:203], v199 offset:61952
	s_add_i32 s6, s80, 0x4000
	s_cmp_lg_u32 s80, 0x10000
	v_fma_f32 v93, v188, s56, v66
	v_fma_f32 v94, v188, s57, v66
	s_cselect_b32 s15, s6, 0
	v_fmamk_f32 v78, v188, 0x41c00000, v66
	v_exp_f32_e32 v127, v127
	v_add_f32_e32 v187, v198, v124
	s_waitcnt lgkmcnt(2)
	v_mfma_f32_32x32x16_bf16 v[34:49], v[162:165], v[178:181], v[34:49]
	ds_read_b64_tr_b16 v[182:183], v199 offset:62464
	ds_read_b64_tr_b16 v[184:185], v199 offset:62976
	v_fmamk_f32 v79, v188, 0x41c80000, v66
	v_fmamk_f32 v95, v188, 0x42640000, v66
	v_cvt_pk_bf16_f32 v155, v124, v125
	v_add_f32_e32 v187, v187, v125
	v_exp_f32_e32 v128, v128
	s_waitcnt lgkmcnt(2)
	v_mfma_f32_32x32x16_bf16 v[50:65], v[174:177], v[200:203], v[50:65]
	ds_read_b64_tr_b16 v[178:179], v199 offset:63488
	ds_read_b64_tr_b16 v[180:181], v199 offset:64000
	v_fmamk_f32 v80, v188, 0x41d00000, v66
	v_fmamk_f32 v96, v188, 0x42680000, v66
	v_exp_f32_e32 v129, v129
	v_add_f32_e32 v187, v187, v126
	v_cvt_pk_bf16_f32 v156, v126, v127
	s_waitcnt lgkmcnt(2)
	v_mfma_f32_32x32x16_bf16 v[50:65], v[170:173], v[182:185], v[50:65]
	ds_read_b64_tr_b16 v[200:201], v199 offset:64512
	ds_read_b64_tr_b16 v[202:203], v199 offset:65024
	v_fmamk_f32 v81, v188, 0x41d80000, v66
	v_fmamk_f32 v97, v188, 0x426c0000, v66
	v_exp_f32_e32 v98, v98
	v_exp_f32_e32 v99, v99
	v_add_f32_e32 v186, v187, v127
	s_waitcnt lgkmcnt(2)
	v_mfma_f32_32x32x16_bf16 v[50:65], v[166:169], v[178:181], v[50:65]
	ds_read_b128 v[182:185], v190 offset:32768
	v_add_f32_e32 v178, v186, v128
	v_cvt_pk_bf16_f32 v157, v128, v129
	v_add_f32_e32 v186, v129, v178
	v_exp_f32_e32 v100, v100
	v_exp_f32_e32 v101, v101
	s_waitcnt lgkmcnt(1)
	v_mfma_f32_32x32x16_bf16 v[50:65], v[162:165], v[200:203], v[50:65]
	ds_read_b128 v[178:181], v190 offset:40960
	v_add_f32_e32 v186, v186, v98
	v_cvt_pk_bf16_f32 v150, v98, v99
	v_add_f32_e32 v198, v99, v186
	v_exp_f32_e32 v102, v102
	v_exp_f32_e32 v103, v103
	s_waitcnt lgkmcnt(1)
	v_mfma_f32_32x32x16_bf16 v[66:81], v[182:185], v[130:133], v[66:81]
	ds_read_b128 v[186:189], v194 offset:32768
	v_add_f32_e32 v182, v198, v100
	v_cvt_pk_bf16_f32 v151, v100, v101
	v_add_f32_e32 v198, v101, v182
	v_exp_f32_e32 v104, v104
	v_exp_f32_e32 v105, v105
	s_waitcnt lgkmcnt(1)
	v_mfma_f32_32x32x16_bf16 v[82:97], v[178:181], v[130:133], v[82:97]
	ds_read_b128 v[182:185], v194 offset:40960
	v_add_f32_e32 v178, v198, v102
	v_cvt_pk_bf16_f32 v152, v102, v103
	v_add_f32_e32 v198, v103, v178
	v_exp_f32_e32 v106, v106
	v_exp_f32_e32 v107, v107
	s_waitcnt lgkmcnt(1)
	v_mfma_f32_32x32x16_bf16 v[66:81], v[186:189], v[134:137], v[66:81]
	ds_read_b128 v[178:181], v195 offset:32768
	v_add_f32_e32 v186, v198, v104
	v_cvt_pk_bf16_f32 v153, v104, v105
	v_add_f32_e32 v198, v105, v186
	v_exp_f32_e32 v108, v108
	v_exp_f32_e32 v109, v109
	s_waitcnt lgkmcnt(1)
	v_mfma_f32_32x32x16_bf16 v[82:97], v[182:185], v[134:137], v[82:97]
	ds_read_b128 v[186:189], v195 offset:40960
	v_add_f32_e32 v182, v198, v106
	v_cvt_pk_bf16_f32 v146, v106, v107
	v_add_f32_e32 v182, v107, v182
	v_exp_f32_e32 v110, v110
	v_exp_f32_e32 v111, v111
	s_waitcnt lgkmcnt(1)
	v_mfma_f32_32x32x16_bf16 v[66:81], v[178:181], v[138:141], v[66:81]
	ds_read_b128 v[198:201], v196 offset:32768
	v_add_f32_e32 v178, v182, v108
	v_cvt_pk_bf16_f32 v147, v108, v109
	v_add_f32_e32 v178, v109, v178
	v_exp_f32_e32 v112, v112
	v_exp_f32_e32 v113, v113
	s_waitcnt lgkmcnt(1)
	v_mfma_f32_32x32x16_bf16 v[82:97], v[186:189], v[138:141], v[82:97]
	ds_read_b128 v[202:205], v196 offset:40960
	v_add_f32_e32 v149, v178, v110
	v_add_f32_e32 v149, v111, v149
	v_add_f32_e32 v178, v112, v149
	v_cvt_pk_bf16_f32 v148, v110, v111
	v_cvt_pk_bf16_f32 v149, v112, v113
	v_add_f32_e32 v187, v113, v178
	s_waitcnt lgkmcnt(1)
	v_mfma_f32_32x32x16_bf16 v[66:81], v[198:201], v[142:145], v[66:81]
	v_add_u32_e32 v199, s15, v240
	ds_read_b64_tr_b16 v[182:183], v199 offset:49152
	ds_read_b64_tr_b16 v[184:185], v199 offset:49664
	s_waitcnt lgkmcnt(2)
	v_mfma_f32_32x32x16_bf16 v[82:97], v[202:205], v[142:145], v[82:97]
	ds_read_b64_tr_b16 v[178:179], v199 offset:50176
	ds_read_b64_tr_b16 v[180:181], v199 offset:50688
	s_add_i32 s6, s15, 0x4000
	s_cmp_lg_u32 s15, 0x10000
	s_cselect_b32 s80, s6, 0
	s_add_i32 s6, s21, 0x4000
	s_cmp_lg_u32 s21, 0x10000
	s_cselect_b32 s81, s6, 0
	s_add_u32 s78, s78, 0x20000
	s_addc_u32 s79, s79, 0
	s_add_u32 s76, s76, 0x20000
	s_addc_u32 s77, s77, 0
	v_add_u32_e32 v197, 0x80, v197
	s_mov_b32 s43, s0
	s_add_i32 s0, s43, 2
	s_waitcnt vmcnt(4) lgkmcnt(0)
	s_barrier
	v_mfma_f32_32x32x16_bf16 v[2:17], v[158:161], v[182:185], v[2:17]
	s_add_i32 s20, s58, s43
	s_cmp_lt_i32 s20, s89
	v_subrev_u32_e32 v198, 64, v197
	s_cselect_b64 s[26:27], -1, 0
	v_cvt_f32_i32_e32 v98, v198
	v_cndmask_b32_e64 v188, -v193, v193, s[26:27]
	ds_read_b64_tr_b16 v[200:201], v199 offset:51200
	ds_read_b64_tr_b16 v[202:203], v199 offset:51712
	v_fma_f32 v114, v188, v98, -v233
	v_exp_f32_e32 v66, v66
	v_exp_f32_e32 v67, v67
	v_fmamk_f32 v98, v188, 0x42000000, v114
	v_add_f32_e32 v115, v188, v114
	v_mfma_f32_32x32x16_bf16 v[2:17], v[154:157], v[178:181], v[2:17]
	ds_read_b64_tr_b16 v[182:183], v199 offset:52224
	ds_read_b64_tr_b16 v[184:185], v199 offset:52736
	v_fmamk_f32 v99, v188, 0x42040000, v114
	v_fma_f32 v116, 2.0, v188, v114
	v_exp_f32_e32 v68, v68
	v_exp_f32_e32 v69, v69
	s_waitcnt lgkmcnt(2)
	v_mfma_f32_32x32x16_bf16 v[2:17], v[150:153], v[200:203], v[2:17]
	ds_read_b64_tr_b16 v[178:179], v199 offset:53248
	ds_read_b64_tr_b16 v[180:181], v199 offset:53760
	v_add_f32_e32 v187, v187, v66
	v_fmamk_f32 v100, v188, 0x42080000, v114
	v_fmamk_f32 v117, v188, 0x40400000, v114
	v_cvt_pk_bf16_f32 v174, v66, v67
	v_add_f32_e32 v187, v67, v187
	v_exp_f32_e32 v70, v70
	s_waitcnt lgkmcnt(2)
	v_mfma_f32_32x32x16_bf16 v[2:17], v[146:149], v[182:185], v[2:17]
	ds_read_b64_tr_b16 v[200:201], v199 offset:54272
	ds_read_b64_tr_b16 v[202:203], v199 offset:54784
	v_fma_f32 v101, v188, s16, v114
	v_fma_f32 v102, v188, s17, v114
	v_fmamk_f32 v118, v188, 0x41000000, v114
	v_exp_f32_e32 v71, v71
	v_add_f32_e32 v187, v187, v68
	s_waitcnt lgkmcnt(2)
	v_mfma_f32_32x32x16_bf16 v[18:33], v[158:161], v[178:181], v[18:33]
	ds_read_b64_tr_b16 v[182:183], v199 offset:55296
	ds_read_b64_tr_b16 v[184:185], v199 offset:55808
	v_fmamk_f32 v119, v188, 0x41100000, v114
	v_fmamk_f32 v103, v188, 0x42240000, v114
	v_cvt_pk_bf16_f32 v175, v68, v69
	v_add_f32_e32 v187, v187, v69
	v_exp_f32_e32 v72, v72
	s_waitcnt lgkmcnt(2)
	v_mfma_f32_32x32x16_bf16 v[18:33], v[154:157], v[200:203], v[18:33]
	ds_read_b64_tr_b16 v[178:179], v199 offset:56320
	ds_read_b64_tr_b16 v[180:181], v199 offset:56832
	v_fmamk_f32 v120, v188, 0x41200000, v114
	v_fmamk_f32 v104, v188, 0x42280000, v114
	v_exp_f32_e32 v73, v73
	v_add_f32_e32 v187, v187, v70
	v_cvt_pk_bf16_f32 v176, v70, v71
	s_waitcnt lgkmcnt(2)
	v_mfma_f32_32x32x16_bf16 v[18:33], v[150:153], v[182:185], v[18:33]
	ds_read_b64_tr_b16 v[200:201], v199 offset:57344
	ds_read_b64_tr_b16 v[202:203], v199 offset:57856
	v_fmamk_f32 v121, v188, 0x41300000, v114
	v_fmamk_f32 v105, v188, 0x422c0000, v114
	v_add_f32_e32 v182, v187, v71
	v_exp_f32_e32 v74, v74
	v_exp_f32_e32 v75, v75
	s_waitcnt lgkmcnt(2)
	v_mfma_f32_32x32x16_bf16 v[18:33], v[146:149], v[178:181], v[18:33]
	ds_read_b64_tr_b16 v[204:205], v199 offset:58368
	ds_read_b64_tr_b16 v[206:207], v199 offset:58880
	v_add_f32_e32 v178, v182, v72
	v_fmamk_f32 v106, v188, 0x42400000, v114
	v_fma_f32 v122, v188, s48, v114
	v_fma_f32 v123, v188, s49, v114
	v_cvt_pk_bf16_f32 v177, v72, v73
	v_add_f32_e32 v187, v73, v178
	s_waitcnt lgkmcnt(2)
	v_mfma_f32_32x32x16_bf16 v[34:49], v[158:161], v[200:203], v[34:49]
	ds_read_b64_tr_b16 v[182:183], v199 offset:59392
	ds_read_b64_tr_b16 v[184:185], v199 offset:59904
	v_fmamk_f32 v107, v188, 0x42440000, v114
	v_fmamk_f32 v124, v188, 0x41900000, v114
	v_exp_f32_e32 v76, v76
	v_exp_f32_e32 v77, v77
	s_waitcnt lgkmcnt(2)
	v_mfma_f32_32x32x16_bf16 v[34:49], v[154:157], v[204:207], v[34:49]
	ds_read_b64_tr_b16 v[178:179], v199 offset:60416
	ds_read_b64_tr_b16 v[180:181], v199 offset:60928
	v_add_f32_e32 v187, v187, v74
	v_fmamk_f32 v108, v188, 0x42480000, v114
	v_fmamk_f32 v125, v188, 0x41980000, v114
	v_cvt_pk_bf16_f32 v170, v74, v75
	v_add_f32_e32 v200, v75, v187
	v_exp_f32_e32 v78, v78
	s_add_u32 s6, s76, s62
	s_addc_u32 s7, s77, s63
	s_add_u32 s26, s6, 0x30000
	s_addc_u32 s27, s7, 0
	s_add_u32 s6, s78, s62
	s_addc_u32 s7, s79, s63
	s_add_u32 s70, s6, 0x30000
	s_addc_u32 s71, s7, 0
	s_add_i32 s6, 0x8000, s59
	s_add_i32 s7, s81, s90
	s_add_u32 s84, s26, 0x8000
	s_addc_u32 s85, s27, 0
	s_add_i32 s15, s6, 0x2000
	s_mov_b32 m0, s6
	s_nop 0
	global_load_lds_dwordx4 v191, s[26:27]
	s_mov_b32 m0, s15
	s_nop 0
	global_load_lds_dwordx4 v191, s[84:85]
	s_mov_b32 m0, s21
	s_add_u32 s26, s70, 0x80
	s_addc_u32 s27, s71, 0
	s_add_i32 s6, s7, 0x2000
	s_mov_b32 m0, s7
	s_nop 0
	global_load_lds_dwordx4 v192, s[70:71]
	s_mov_b32 m0, s6
	s_nop 0
	global_load_lds_dwordx4 v192, s[26:27]
	s_mov_b32 m0, s15
	s_waitcnt lgkmcnt(2)
	v_mfma_f32_32x32x16_bf16 v[34:49], v[150:153], v[182:185], v[34:49]
	ds_read_b64_tr_b16 v[202:203], v199 offset:61440
	ds_read_b64_tr_b16 v[204:205], v199 offset:61952
	v_fma_f32 v109, v188, s56, v114
	v_fma_f32 v110, v188, s57, v114
	v_fmamk_f32 v126, v188, 0x41c00000, v114
	v_exp_f32_e32 v79, v79
	v_add_f32_e32 v187, v200, v76
	s_waitcnt lgkmcnt(2)
	v_mfma_f32_32x32x16_bf16 v[34:49], v[146:149], v[178:181], v[34:49]
	ds_read_b64_tr_b16 v[182:183], v199 offset:62464
	ds_read_b64_tr_b16 v[184:185], v199 offset:62976
	v_fmamk_f32 v127, v188, 0x41c80000, v114
	v_fmamk_f32 v111, v188, 0x42640000, v114
	v_cvt_pk_bf16_f32 v171, v76, v77
	v_add_f32_e32 v187, v187, v77
	v_exp_f32_e32 v80, v80
	s_waitcnt lgkmcnt(2)
	v_mfma_f32_32x32x16_bf16 v[50:65], v[158:161], v[202:205], v[50:65]
	ds_read_b64_tr_b16 v[178:179], v199 offset:63488
	ds_read_b64_tr_b16 v[180:181], v199 offset:64000
	v_fmamk_f32 v128, v188, 0x41d00000, v114
	v_fmamk_f32 v112, v188, 0x42680000, v114
	v_exp_f32_e32 v81, v81
	v_add_f32_e32 v187, v187, v78
	v_cvt_pk_bf16_f32 v172, v78, v79
	s_waitcnt lgkmcnt(2)
	v_mfma_f32_32x32x16_bf16 v[50:65], v[154:157], v[182:185], v[50:65]
	ds_read_b64_tr_b16 v[200:201], v199 offset:64512
	ds_read_b64_tr_b16 v[202:203], v199 offset:65024
	v_fmamk_f32 v129, v188, 0x41d80000, v114
	v_fmamk_f32 v113, v188, 0x426c0000, v114
	v_exp_f32_e32 v82, v82
	v_exp_f32_e32 v83, v83
	v_add_f32_e32 v186, v187, v79
	s_waitcnt lgkmcnt(2)
	v_mfma_f32_32x32x16_bf16 v[50:65], v[150:153], v[178:181], v[50:65]
	ds_read_b128 v[182:185], v190
	v_add_f32_e32 v178, v186, v80
	v_cvt_pk_bf16_f32 v173, v80, v81
	v_add_f32_e32 v186, v81, v178
	v_exp_f32_e32 v84, v84
	v_exp_f32_e32 v85, v85
	s_waitcnt lgkmcnt(1)
	v_mfma_f32_32x32x16_bf16 v[50:65], v[146:149], v[200:203], v[50:65]
	ds_read_b128 v[178:181], v190 offset:8192
	v_add_f32_e32 v186, v186, v82
	v_cvt_pk_bf16_f32 v166, v82, v83
	v_add_f32_e32 v199, v83, v186
	v_exp_f32_e32 v86, v86
	v_exp_f32_e32 v87, v87
	s_waitcnt lgkmcnt(1)
	v_mfma_f32_32x32x16_bf16 v[114:129], v[182:185], v[130:133], v[114:129]
	ds_read_b128 v[186:189], v194
	v_add_f32_e32 v182, v199, v84
	v_cvt_pk_bf16_f32 v167, v84, v85
	v_add_f32_e32 v199, v85, v182
	v_exp_f32_e32 v88, v88
	v_exp_f32_e32 v89, v89
	s_waitcnt lgkmcnt(1)
	v_mfma_f32_32x32x16_bf16 v[98:113], v[178:181], v[130:133], v[98:113]
	ds_read_b128 v[182:185], v194 offset:8192
	v_add_f32_e32 v178, v199, v86
	v_cvt_pk_bf16_f32 v168, v86, v87
	v_add_f32_e32 v199, v87, v178
	v_exp_f32_e32 v90, v90
	v_exp_f32_e32 v91, v91
	s_waitcnt lgkmcnt(1)
	v_mfma_f32_32x32x16_bf16 v[114:129], v[186:189], v[134:137], v[114:129]
	ds_read_b128 v[178:181], v195
	v_add_f32_e32 v186, v199, v88
	v_cvt_pk_bf16_f32 v169, v88, v89
	v_add_f32_e32 v199, v89, v186
	v_exp_f32_e32 v92, v92
	v_exp_f32_e32 v93, v93
	s_waitcnt lgkmcnt(1)
	v_mfma_f32_32x32x16_bf16 v[98:113], v[182:185], v[134:137], v[98:113]
	ds_read_b128 v[186:189], v195 offset:8192
	v_add_f32_e32 v182, v199, v90
	v_cvt_pk_bf16_f32 v162, v90, v91
	v_add_f32_e32 v182, v91, v182
	v_exp_f32_e32 v94, v94
	v_exp_f32_e32 v95, v95
	s_waitcnt lgkmcnt(1)
	v_mfma_f32_32x32x16_bf16 v[114:129], v[178:181], v[138:141], v[114:129]
	ds_read_b128 v[200:203], v196
	v_add_f32_e32 v178, v182, v92
	v_cvt_pk_bf16_f32 v163, v92, v93
	v_add_f32_e32 v178, v93, v178
	v_exp_f32_e32 v96, v96
	v_exp_f32_e32 v97, v97
	s_waitcnt lgkmcnt(1)
	v_mfma_f32_32x32x16_bf16 v[98:113], v[186:189], v[138:141], v[98:113]
	ds_read_b128 v[204:207], v196 offset:8192
	v_add_f32_e32 v165, v178, v94
	v_add_f32_e32 v165, v95, v165
	v_add_f32_e32 v178, v96, v165
	v_cvt_pk_bf16_f32 v164, v94, v95
	v_cvt_pk_bf16_f32 v165, v96, v97
	v_add_f32_e32 v187, v97, v178
	s_waitcnt lgkmcnt(1)
	v_mfma_f32_32x32x16_bf16 v[114:129], v[200:203], v[142:145], v[114:129]
	v_add_u32_e32 v199, s80, v240
	ds_read_b64_tr_b16 v[182:183], v199 offset:49152
	ds_read_b64_tr_b16 v[184:185], v199 offset:49664
	s_waitcnt lgkmcnt(2)
	v_mfma_f32_32x32x16_bf16 v[98:113], v[204:207], v[142:145], v[98:113]
	ds_read_b64_tr_b16 v[178:179], v199 offset:50176
	ds_read_b64_tr_b16 v[180:181], v199 offset:50688
	s_waitcnt vmcnt(4) lgkmcnt(0)
	s_barrier
	v_mfma_f32_32x32x16_bf16 v[2:17], v[174:177], v[182:185], v[2:17]
	s_add_i32 s6, s81, 0x4000
	s_cmp_lg_u32 s81, 0x10000
	s_cselect_b32 s21, s6, 0
	s_add_i32 s20, s20, 1
	s_cmp_lt_i32 s20, s89
	s_cselect_b64 s[6:7], -1, 0
	v_cvt_f32_i32_e32 v66, v197
	v_cndmask_b32_e64 v188, -v193, v193, s[6:7]
	ds_read_b64_tr_b16 v[200:201], v199 offset:51200
	ds_read_b64_tr_b16 v[202:203], v199 offset:51712
	v_fma_f32 v66, v188, v66, -v233
	v_exp_f32_e32 v114, v114
	v_exp_f32_e32 v115, v115
	v_fmamk_f32 v82, v188, 0x42000000, v66
	v_add_f32_e32 v67, v188, v66
	v_mfma_f32_32x32x16_bf16 v[2:17], v[170:173], v[178:181], v[2:17]
	ds_read_b64_tr_b16 v[182:183], v199 offset:52224
	ds_read_b64_tr_b16 v[184:185], v199 offset:52736
	v_fmamk_f32 v83, v188, 0x42040000, v66
	v_fma_f32 v68, 2.0, v188, v66
	v_exp_f32_e32 v116, v116
	v_exp_f32_e32 v117, v117
	s_waitcnt lgkmcnt(2)
	v_mfma_f32_32x32x16_bf16 v[2:17], v[166:169], v[200:203], v[2:17]
	ds_read_b64_tr_b16 v[178:179], v199 offset:53248
	ds_read_b64_tr_b16 v[180:181], v199 offset:53760
	v_add_f32_e32 v187, v187, v114
	v_fmamk_f32 v84, v188, 0x42080000, v66
	v_fmamk_f32 v69, v188, 0x40400000, v66
	v_cvt_pk_bf16_f32 v158, v114, v115
	v_add_f32_e32 v187, v115, v187
	v_exp_f32_e32 v118, v118
	s_waitcnt lgkmcnt(2)
	v_mfma_f32_32x32x16_bf16 v[2:17], v[162:165], v[182:185], v[2:17]
	ds_read_b64_tr_b16 v[200:201], v199 offset:54272
	ds_read_b64_tr_b16 v[202:203], v199 offset:54784
	v_fma_f32 v85, v188, s16, v66
	v_fma_f32 v86, v188, s17, v66
	v_fmamk_f32 v70, v188, 0x41000000, v66
	v_exp_f32_e32 v119, v119
	v_add_f32_e32 v187, v187, v116
	s_waitcnt lgkmcnt(2)
	v_mfma_f32_32x32x16_bf16 v[18:33], v[174:177], v[178:181], v[18:33]
	ds_read_b64_tr_b16 v[182:183], v199 offset:55296
	ds_read_b64_tr_b16 v[184:185], v199 offset:55808
	v_fmamk_f32 v71, v188, 0x41100000, v66
	v_fmamk_f32 v87, v188, 0x42240000, v66
	v_cvt_pk_bf16_f32 v159, v116, v117
	v_add_f32_e32 v187, v187, v117
	v_exp_f32_e32 v120, v120
	s_waitcnt lgkmcnt(2)
	v_mfma_f32_32x32x16_bf16 v[18:33], v[170:173], v[200:203], v[18:33]
	ds_read_b64_tr_b16 v[178:179], v199 offset:56320
	ds_read_b64_tr_b16 v[180:181], v199 offset:56832
	v_fmamk_f32 v72, v188, 0x41200000, v66
	v_fmamk_f32 v88, v188, 0x42280000, v66
	v_exp_f32_e32 v121, v121
	v_add_f32_e32 v187, v187, v118
	v_cvt_pk_bf16_f32 v160, v118, v119
	s_waitcnt lgkmcnt(2)
	v_mfma_f32_32x32x16_bf16 v[18:33], v[166:169], v[182:185], v[18:33]
	ds_read_b64_tr_b16 v[200:201], v199 offset:57344
	ds_read_b64_tr_b16 v[202:203], v199 offset:57856
	v_fmamk_f32 v73, v188, 0x41300000, v66
	v_fmamk_f32 v89, v188, 0x422c0000, v66
	v_add_f32_e32 v182, v187, v119
	v_exp_f32_e32 v122, v122
	v_exp_f32_e32 v123, v123
	s_waitcnt lgkmcnt(2)
	v_mfma_f32_32x32x16_bf16 v[18:33], v[162:165], v[178:181], v[18:33]
	ds_read_b64_tr_b16 v[204:205], v199 offset:58368
	ds_read_b64_tr_b16 v[206:207], v199 offset:58880
	v_add_f32_e32 v178, v182, v120
	v_fmamk_f32 v90, v188, 0x42400000, v66
	v_fma_f32 v74, v188, s48, v66
	v_fma_f32 v75, v188, s49, v66
	v_cvt_pk_bf16_f32 v161, v120, v121
	v_add_f32_e32 v187, v121, v178
	s_waitcnt lgkmcnt(2)
	v_mfma_f32_32x32x16_bf16 v[34:49], v[174:177], v[200:203], v[34:49]
	ds_read_b64_tr_b16 v[182:183], v199 offset:59392
	ds_read_b64_tr_b16 v[184:185], v199 offset:59904
	v_fmamk_f32 v91, v188, 0x42440000, v66
	v_fmamk_f32 v76, v188, 0x41900000, v66
	v_exp_f32_e32 v124, v124
	v_exp_f32_e32 v125, v125
	s_waitcnt lgkmcnt(2)
	v_mfma_f32_32x32x16_bf16 v[34:49], v[170:173], v[204:207], v[34:49]
	ds_read_b64_tr_b16 v[178:179], v199 offset:60416
	ds_read_b64_tr_b16 v[180:181], v199 offset:60928
	v_add_f32_e32 v187, v187, v122
	v_fmamk_f32 v92, v188, 0x42480000, v66
	v_fmamk_f32 v77, v188, 0x41980000, v66
	v_cvt_pk_bf16_f32 v154, v122, v123
	v_add_f32_e32 v198, v123, v187
	v_exp_f32_e32 v126, v126
	s_add_u32 s6, s76, s62
	s_addc_u32 s7, s77, s63
	s_add_u32 s6, s6, 0x40000
	s_addc_u32 s7, s7, 0
	s_add_u32 s15, s78, s62
	s_addc_u32 s20, s79, s63
	s_add_u32 s24, s15, 0x40000
	s_addc_u32 s25, s20, 0
	s_add_i32 s15, 0, s59
	s_add_i32 s20, s21, s90
	s_add_u32 s26, s6, 0x8000
	s_addc_u32 s27, s7, 0
	s_add_i32 s68, s15, 0x2000
	s_mov_b32 m0, s15
	s_nop 0
	global_load_lds_dwordx4 v191, s[6:7]
	s_mov_b32 m0, s68
	s_nop 0
	global_load_lds_dwordx4 v191, s[26:27]
	s_mov_b32 m0, s69
	s_add_u32 s6, s24, 0x80
	s_addc_u32 s7, s25, 0
	s_add_i32 s15, s20, 0x2000
	s_mov_b32 m0, s20
	s_nop 0
	global_load_lds_dwordx4 v192, s[24:25]
	s_mov_b32 m0, s15
	s_nop 0
	global_load_lds_dwordx4 v192, s[6:7]
	s_mov_b32 m0, s26
	s_waitcnt lgkmcnt(2)
	v_mfma_f32_32x32x16_bf16 v[34:49], v[166:169], v[182:185], v[34:49]
	ds_read_b64_tr_b16 v[200:201], v199 offset:61440
	ds_read_b64_tr_b16 v[202:203], v199 offset:61952
	s_add_i32 s6, s80, 0x4000
	s_cmp_lg_u32 s80, 0x10000
	v_fma_f32 v93, v188, s56, v66
	v_fma_f32 v94, v188, s57, v66
	s_cselect_b32 s15, s6, 0
	v_fmamk_f32 v78, v188, 0x41c00000, v66
	v_exp_f32_e32 v127, v127
	v_add_f32_e32 v187, v198, v124
	s_waitcnt lgkmcnt(2)
	v_mfma_f32_32x32x16_bf16 v[34:49], v[162:165], v[178:181], v[34:49]
	ds_read_b64_tr_b16 v[182:183], v199 offset:62464
	ds_read_b64_tr_b16 v[184:185], v199 offset:62976
	v_fmamk_f32 v79, v188, 0x41c80000, v66
	v_fmamk_f32 v95, v188, 0x42640000, v66
	v_cvt_pk_bf16_f32 v155, v124, v125
	v_add_f32_e32 v187, v187, v125
	v_exp_f32_e32 v128, v128
	s_waitcnt lgkmcnt(2)
	v_mfma_f32_32x32x16_bf16 v[50:65], v[174:177], v[200:203], v[50:65]
	ds_read_b64_tr_b16 v[178:179], v199 offset:63488
	ds_read_b64_tr_b16 v[180:181], v199 offset:64000
	v_fmamk_f32 v80, v188, 0x41d00000, v66
	v_fmamk_f32 v96, v188, 0x42680000, v66
	v_exp_f32_e32 v129, v129
	v_add_f32_e32 v187, v187, v126
	v_cvt_pk_bf16_f32 v156, v126, v127
	s_waitcnt lgkmcnt(2)
	v_mfma_f32_32x32x16_bf16 v[50:65], v[170:173], v[182:185], v[50:65]
	ds_read_b64_tr_b16 v[200:201], v199 offset:64512
	ds_read_b64_tr_b16 v[202:203], v199 offset:65024
	v_fmamk_f32 v81, v188, 0x41d80000, v66
	v_fmamk_f32 v97, v188, 0x426c0000, v66
	v_exp_f32_e32 v98, v98
	v_exp_f32_e32 v99, v99
	v_add_f32_e32 v186, v187, v127
	s_waitcnt lgkmcnt(2)
	v_mfma_f32_32x32x16_bf16 v[50:65], v[166:169], v[178:181], v[50:65]
	ds_read_b128 v[182:185], v190 offset:16384
	v_add_f32_e32 v178, v186, v128
	v_cvt_pk_bf16_f32 v157, v128, v129
	v_add_f32_e32 v186, v129, v178
	v_exp_f32_e32 v100, v100
	v_exp_f32_e32 v101, v101
	s_waitcnt lgkmcnt(1)
	v_mfma_f32_32x32x16_bf16 v[50:65], v[162:165], v[200:203], v[50:65]
	ds_read_b128 v[178:181], v190 offset:24576
	v_add_f32_e32 v186, v186, v98
	v_cvt_pk_bf16_f32 v150, v98, v99
	v_add_f32_e32 v198, v99, v186
	v_exp_f32_e32 v102, v102
	v_exp_f32_e32 v103, v103
	s_waitcnt lgkmcnt(1)
	v_mfma_f32_32x32x16_bf16 v[66:81], v[182:185], v[130:133], v[66:81]
	ds_read_b128 v[186:189], v194 offset:16384
	v_add_f32_e32 v182, v198, v100
	v_cvt_pk_bf16_f32 v151, v100, v101
	v_add_f32_e32 v198, v101, v182
	v_exp_f32_e32 v104, v104
	v_exp_f32_e32 v105, v105
	s_waitcnt lgkmcnt(1)
	v_mfma_f32_32x32x16_bf16 v[82:97], v[178:181], v[130:133], v[82:97]
	ds_read_b128 v[182:185], v194 offset:24576
	v_add_f32_e32 v178, v198, v102
	v_cvt_pk_bf16_f32 v152, v102, v103
	v_add_f32_e32 v198, v103, v178
	v_exp_f32_e32 v106, v106
	v_exp_f32_e32 v107, v107
	s_waitcnt lgkmcnt(1)
	v_mfma_f32_32x32x16_bf16 v[66:81], v[186:189], v[134:137], v[66:81]
	ds_read_b128 v[178:181], v195 offset:16384
	v_add_f32_e32 v186, v198, v104
	v_cvt_pk_bf16_f32 v153, v104, v105
	v_add_f32_e32 v198, v105, v186
	v_exp_f32_e32 v108, v108
	v_exp_f32_e32 v109, v109
	s_waitcnt lgkmcnt(1)
	v_mfma_f32_32x32x16_bf16 v[82:97], v[182:185], v[134:137], v[82:97]
	ds_read_b128 v[186:189], v195 offset:24576
	v_add_f32_e32 v182, v198, v106
	v_cvt_pk_bf16_f32 v146, v106, v107
	v_add_f32_e32 v182, v107, v182
	v_exp_f32_e32 v110, v110
	v_exp_f32_e32 v111, v111
	s_waitcnt lgkmcnt(1)
	v_mfma_f32_32x32x16_bf16 v[66:81], v[178:181], v[138:141], v[66:81]
	ds_read_b128 v[198:201], v196 offset:16384
	v_add_f32_e32 v178, v182, v108
	v_cvt_pk_bf16_f32 v147, v108, v109
	v_add_f32_e32 v178, v109, v178
	v_exp_f32_e32 v112, v112
	v_exp_f32_e32 v113, v113
	s_waitcnt lgkmcnt(1)
	v_mfma_f32_32x32x16_bf16 v[82:97], v[186:189], v[138:141], v[82:97]
	ds_read_b128 v[202:205], v196 offset:24576
	v_add_f32_e32 v149, v178, v110
	v_add_f32_e32 v149, v111, v149
	v_add_f32_e32 v178, v112, v149
	v_cvt_pk_bf16_f32 v148, v110, v111
	v_cvt_pk_bf16_f32 v149, v112, v113
	v_add_f32_e32 v187, v113, v178
	s_waitcnt lgkmcnt(1)
	v_mfma_f32_32x32x16_bf16 v[66:81], v[198:201], v[142:145], v[66:81]
	v_add_u32_e32 v199, s15, v240
	ds_read_b64_tr_b16 v[182:183], v199 offset:49152
	ds_read_b64_tr_b16 v[184:185], v199 offset:49664
	s_waitcnt lgkmcnt(2)
	v_mfma_f32_32x32x16_bf16 v[82:97], v[202:205], v[142:145], v[82:97]
	ds_read_b64_tr_b16 v[178:179], v199 offset:50176
	ds_read_b64_tr_b16 v[180:181], v199 offset:50688
	s_add_i32 s6, s15, 0x4000
	s_cmp_lg_u32 s15, 0x10000
	s_cselect_b32 s80, s6, 0
	s_add_i32 s6, s21, 0x4000
	s_cmp_lg_u32 s21, 0x10000
	s_cselect_b32 s81, s6, 0
	s_add_u32 s78, s78, 0x20000
	s_addc_u32 s79, s79, 0
	s_add_u32 s76, s76, 0x20000
	s_addc_u32 s77, s77, 0
	v_add_u32_e32 v197, 0x80, v197
	s_mov_b32 s43, s0
	s_add_i32 s0, s43, 2
	s_waitcnt vmcnt(4) lgkmcnt(0)
	s_barrier
	v_mfma_f32_32x32x16_bf16 v[2:17], v[158:161], v[182:185], v[2:17]
	s_add_i32 s20, s58, s43
	s_cmp_lt_i32 s20, s89
	v_subrev_u32_e32 v198, 64, v197
	s_cselect_b64 s[26:27], -1, 0
	v_cvt_f32_i32_e32 v98, v198
	v_cndmask_b32_e64 v188, -v193, v193, s[26:27]
	ds_read_b64_tr_b16 v[200:201], v199 offset:51200
	ds_read_b64_tr_b16 v[202:203], v199 offset:51712
	v_fma_f32 v114, v188, v98, -v233
	v_exp_f32_e32 v66, v66
	v_exp_f32_e32 v67, v67
	v_fmamk_f32 v98, v188, 0x42000000, v114
	v_add_f32_e32 v115, v188, v114
	v_mfma_f32_32x32x16_bf16 v[2:17], v[154:157], v[178:181], v[2:17]
	ds_read_b64_tr_b16 v[182:183], v199 offset:52224
	ds_read_b64_tr_b16 v[184:185], v199 offset:52736
	v_fmamk_f32 v99, v188, 0x42040000, v114
	v_fma_f32 v116, 2.0, v188, v114
	v_exp_f32_e32 v68, v68
	v_exp_f32_e32 v69, v69
	s_waitcnt lgkmcnt(2)
	v_mfma_f32_32x32x16_bf16 v[2:17], v[150:153], v[200:203], v[2:17]
	ds_read_b64_tr_b16 v[178:179], v199 offset:53248
	ds_read_b64_tr_b16 v[180:181], v199 offset:53760
	v_add_f32_e32 v187, v187, v66
	v_fmamk_f32 v100, v188, 0x42080000, v114
	v_fmamk_f32 v117, v188, 0x40400000, v114
	v_cvt_pk_bf16_f32 v174, v66, v67
	v_add_f32_e32 v187, v67, v187
	v_exp_f32_e32 v70, v70
	s_waitcnt lgkmcnt(2)
	v_mfma_f32_32x32x16_bf16 v[2:17], v[146:149], v[182:185], v[2:17]
	ds_read_b64_tr_b16 v[200:201], v199 offset:54272
	ds_read_b64_tr_b16 v[202:203], v199 offset:54784
	v_fma_f32 v101, v188, s16, v114
	v_fma_f32 v102, v188, s17, v114
	v_fmamk_f32 v118, v188, 0x41000000, v114
	v_exp_f32_e32 v71, v71
	v_add_f32_e32 v187, v187, v68
	s_waitcnt lgkmcnt(2)
	v_mfma_f32_32x32x16_bf16 v[18:33], v[158:161], v[178:181], v[18:33]
	ds_read_b64_tr_b16 v[182:183], v199 offset:55296
	ds_read_b64_tr_b16 v[184:185], v199 offset:55808
	v_fmamk_f32 v119, v188, 0x41100000, v114
	v_fmamk_f32 v103, v188, 0x42240000, v114
	v_cvt_pk_bf16_f32 v175, v68, v69
	v_add_f32_e32 v187, v187, v69
	v_exp_f32_e32 v72, v72
	s_waitcnt lgkmcnt(2)
	v_mfma_f32_32x32x16_bf16 v[18:33], v[154:157], v[200:203], v[18:33]
	ds_read_b64_tr_b16 v[178:179], v199 offset:56320
	ds_read_b64_tr_b16 v[180:181], v199 offset:56832
	v_fmamk_f32 v120, v188, 0x41200000, v114
	v_fmamk_f32 v104, v188, 0x42280000, v114
	v_exp_f32_e32 v73, v73
	v_add_f32_e32 v187, v187, v70
	v_cvt_pk_bf16_f32 v176, v70, v71
	s_waitcnt lgkmcnt(2)
	v_mfma_f32_32x32x16_bf16 v[18:33], v[150:153], v[182:185], v[18:33]
	ds_read_b64_tr_b16 v[200:201], v199 offset:57344
	ds_read_b64_tr_b16 v[202:203], v199 offset:57856
	v_fmamk_f32 v121, v188, 0x41300000, v114
	v_fmamk_f32 v105, v188, 0x422c0000, v114
	v_add_f32_e32 v182, v187, v71
	v_exp_f32_e32 v74, v74
	v_exp_f32_e32 v75, v75
	s_waitcnt lgkmcnt(2)
	v_mfma_f32_32x32x16_bf16 v[18:33], v[146:149], v[178:181], v[18:33]
	ds_read_b64_tr_b16 v[204:205], v199 offset:58368
	ds_read_b64_tr_b16 v[206:207], v199 offset:58880
	v_add_f32_e32 v178, v182, v72
	v_fmamk_f32 v106, v188, 0x42400000, v114
	v_fma_f32 v122, v188, s48, v114
	v_fma_f32 v123, v188, s49, v114
	v_cvt_pk_bf16_f32 v177, v72, v73
	v_add_f32_e32 v187, v73, v178
	s_waitcnt lgkmcnt(2)
	v_mfma_f32_32x32x16_bf16 v[34:49], v[158:161], v[200:203], v[34:49]
	ds_read_b64_tr_b16 v[182:183], v199 offset:59392
	ds_read_b64_tr_b16 v[184:185], v199 offset:59904
	v_fmamk_f32 v107, v188, 0x42440000, v114
	v_fmamk_f32 v124, v188, 0x41900000, v114
	v_exp_f32_e32 v76, v76
	v_exp_f32_e32 v77, v77
	s_waitcnt lgkmcnt(2)
	v_mfma_f32_32x32x16_bf16 v[34:49], v[154:157], v[204:207], v[34:49]
	ds_read_b64_tr_b16 v[178:179], v199 offset:60416
	ds_read_b64_tr_b16 v[180:181], v199 offset:60928
	v_add_f32_e32 v187, v187, v74
	v_fmamk_f32 v108, v188, 0x42480000, v114
	v_fmamk_f32 v125, v188, 0x41980000, v114
	v_cvt_pk_bf16_f32 v170, v74, v75
	v_add_f32_e32 v200, v75, v187
	v_exp_f32_e32 v78, v78
	s_add_u32 s6, s76, s62
	s_addc_u32 s7, s77, s63
	s_add_u32 s26, s6, 0x30000
	s_addc_u32 s27, s7, 0
	s_add_u32 s6, s78, s62
	s_addc_u32 s7, s79, s63
	s_add_u32 s70, s6, 0x30000
	s_addc_u32 s71, s7, 0
	s_add_i32 s6, 0x4000, s59
	s_add_i32 s7, s81, s90
	s_add_u32 s84, s26, 0x8000
	s_addc_u32 s85, s27, 0
	s_add_i32 s15, s6, 0x2000
	s_mov_b32 m0, s6
	s_nop 0
	global_load_lds_dwordx4 v191, s[26:27]
	s_mov_b32 m0, s15
	s_nop 0
	global_load_lds_dwordx4 v191, s[84:85]
	s_mov_b32 m0, s21
	s_add_u32 s26, s70, 0x80
	s_addc_u32 s27, s71, 0
	s_add_i32 s6, s7, 0x2000
	s_mov_b32 m0, s7
	s_nop 0
	global_load_lds_dwordx4 v192, s[70:71]
	s_mov_b32 m0, s6
	s_nop 0
	global_load_lds_dwordx4 v192, s[26:27]
	s_mov_b32 m0, s15
	s_waitcnt lgkmcnt(2)
	v_mfma_f32_32x32x16_bf16 v[34:49], v[150:153], v[182:185], v[34:49]
	ds_read_b64_tr_b16 v[202:203], v199 offset:61440
	ds_read_b64_tr_b16 v[204:205], v199 offset:61952
	v_fma_f32 v109, v188, s56, v114
	v_fma_f32 v110, v188, s57, v114
	v_fmamk_f32 v126, v188, 0x41c00000, v114
	v_exp_f32_e32 v79, v79
	v_add_f32_e32 v187, v200, v76
	s_waitcnt lgkmcnt(2)
	v_mfma_f32_32x32x16_bf16 v[34:49], v[146:149], v[178:181], v[34:49]
	ds_read_b64_tr_b16 v[182:183], v199 offset:62464
	ds_read_b64_tr_b16 v[184:185], v199 offset:62976
	v_fmamk_f32 v127, v188, 0x41c80000, v114
	v_fmamk_f32 v111, v188, 0x42640000, v114
	v_cvt_pk_bf16_f32 v171, v76, v77
	v_add_f32_e32 v187, v187, v77
	v_exp_f32_e32 v80, v80
	s_waitcnt lgkmcnt(2)
	v_mfma_f32_32x32x16_bf16 v[50:65], v[158:161], v[202:205], v[50:65]
	ds_read_b64_tr_b16 v[178:179], v199 offset:63488
	ds_read_b64_tr_b16 v[180:181], v199 offset:64000
	v_fmamk_f32 v128, v188, 0x41d00000, v114
	v_fmamk_f32 v112, v188, 0x42680000, v114
	v_exp_f32_e32 v81, v81
	v_add_f32_e32 v187, v187, v78
	v_cvt_pk_bf16_f32 v172, v78, v79
	s_waitcnt lgkmcnt(2)
	v_mfma_f32_32x32x16_bf16 v[50:65], v[154:157], v[182:185], v[50:65]
	ds_read_b64_tr_b16 v[200:201], v199 offset:64512
	ds_read_b64_tr_b16 v[202:203], v199 offset:65024
	v_fmamk_f32 v129, v188, 0x41d80000, v114
	v_fmamk_f32 v113, v188, 0x426c0000, v114
	v_exp_f32_e32 v82, v82
	v_exp_f32_e32 v83, v83
	v_add_f32_e32 v186, v187, v79
	s_waitcnt lgkmcnt(2)
	v_mfma_f32_32x32x16_bf16 v[50:65], v[150:153], v[178:181], v[50:65]
	ds_read_b128 v[182:185], v190 offset:32768
	v_add_f32_e32 v178, v186, v80
	v_cvt_pk_bf16_f32 v173, v80, v81
	v_add_f32_e32 v186, v81, v178
	v_exp_f32_e32 v84, v84
	v_exp_f32_e32 v85, v85
	s_waitcnt lgkmcnt(1)
	v_mfma_f32_32x32x16_bf16 v[50:65], v[146:149], v[200:203], v[50:65]
	ds_read_b128 v[178:181], v190 offset:40960
	v_add_f32_e32 v186, v186, v82
	v_cvt_pk_bf16_f32 v166, v82, v83
	v_add_f32_e32 v199, v83, v186
	v_exp_f32_e32 v86, v86
	v_exp_f32_e32 v87, v87
	s_waitcnt lgkmcnt(1)
	v_mfma_f32_32x32x16_bf16 v[114:129], v[182:185], v[130:133], v[114:129]
	ds_read_b128 v[186:189], v194 offset:32768
	v_add_f32_e32 v182, v199, v84
	v_cvt_pk_bf16_f32 v167, v84, v85
	v_add_f32_e32 v199, v85, v182
	v_exp_f32_e32 v88, v88
	v_exp_f32_e32 v89, v89
	s_waitcnt lgkmcnt(1)
	v_mfma_f32_32x32x16_bf16 v[98:113], v[178:181], v[130:133], v[98:113]
	ds_read_b128 v[182:185], v194 offset:40960
	v_add_f32_e32 v178, v199, v86
	v_cvt_pk_bf16_f32 v168, v86, v87
	v_add_f32_e32 v199, v87, v178
	v_exp_f32_e32 v90, v90
	v_exp_f32_e32 v91, v91
	s_waitcnt lgkmcnt(1)
	v_mfma_f32_32x32x16_bf16 v[114:129], v[186:189], v[134:137], v[114:129]
	ds_read_b128 v[178:181], v195 offset:32768
	v_add_f32_e32 v186, v199, v88
	v_cvt_pk_bf16_f32 v169, v88, v89
	v_add_f32_e32 v199, v89, v186
	v_exp_f32_e32 v92, v92
	v_exp_f32_e32 v93, v93
	s_waitcnt lgkmcnt(1)
	v_mfma_f32_32x32x16_bf16 v[98:113], v[182:185], v[134:137], v[98:113]
	ds_read_b128 v[186:189], v195 offset:40960
	v_add_f32_e32 v182, v199, v90
	v_cvt_pk_bf16_f32 v162, v90, v91
	v_add_f32_e32 v182, v91, v182
	v_exp_f32_e32 v94, v94
	v_exp_f32_e32 v95, v95
	s_waitcnt lgkmcnt(1)
	v_mfma_f32_32x32x16_bf16 v[114:129], v[178:181], v[138:141], v[114:129]
	ds_read_b128 v[200:203], v196 offset:32768
	v_add_f32_e32 v178, v182, v92
	v_cvt_pk_bf16_f32 v163, v92, v93
	v_add_f32_e32 v178, v93, v178
	v_exp_f32_e32 v96, v96
	v_exp_f32_e32 v97, v97
	s_waitcnt lgkmcnt(1)
	v_mfma_f32_32x32x16_bf16 v[98:113], v[186:189], v[138:141], v[98:113]
	ds_read_b128 v[204:207], v196 offset:40960
	v_add_f32_e32 v165, v178, v94
	v_add_f32_e32 v165, v95, v165
	v_add_f32_e32 v178, v96, v165
	v_cvt_pk_bf16_f32 v164, v94, v95
	v_cvt_pk_bf16_f32 v165, v96, v97
	v_add_f32_e32 v187, v97, v178
	s_waitcnt lgkmcnt(1)
	v_mfma_f32_32x32x16_bf16 v[114:129], v[200:203], v[142:145], v[114:129]
	v_add_u32_e32 v199, s80, v240
	ds_read_b64_tr_b16 v[182:183], v199 offset:49152
	ds_read_b64_tr_b16 v[184:185], v199 offset:49664
	s_waitcnt lgkmcnt(2)
	v_mfma_f32_32x32x16_bf16 v[98:113], v[204:207], v[142:145], v[98:113]
	ds_read_b64_tr_b16 v[178:179], v199 offset:50176
	ds_read_b64_tr_b16 v[180:181], v199 offset:50688
	s_waitcnt vmcnt(4) lgkmcnt(0)
	s_barrier
	v_mfma_f32_32x32x16_bf16 v[2:17], v[174:177], v[182:185], v[2:17]
	s_add_i32 s6, s81, 0x4000
	s_cmp_lg_u32 s81, 0x10000
	s_cselect_b32 s21, s6, 0
	s_add_i32 s20, s20, 1
	s_cmp_lt_i32 s20, s89
	s_cselect_b64 s[6:7], -1, 0
	v_cvt_f32_i32_e32 v66, v197
	v_cndmask_b32_e64 v188, -v193, v193, s[6:7]
	ds_read_b64_tr_b16 v[200:201], v199 offset:51200
	ds_read_b64_tr_b16 v[202:203], v199 offset:51712
	v_fma_f32 v66, v188, v66, -v233
	v_exp_f32_e32 v114, v114
	v_exp_f32_e32 v115, v115
	v_fmamk_f32 v82, v188, 0x42000000, v66
	v_add_f32_e32 v67, v188, v66
	v_mfma_f32_32x32x16_bf16 v[2:17], v[170:173], v[178:181], v[2:17]
	ds_read_b64_tr_b16 v[182:183], v199 offset:52224
	ds_read_b64_tr_b16 v[184:185], v199 offset:52736
	v_fmamk_f32 v83, v188, 0x42040000, v66
	v_fma_f32 v68, 2.0, v188, v66
	v_exp_f32_e32 v116, v116
	v_exp_f32_e32 v117, v117
	s_waitcnt lgkmcnt(2)
	v_mfma_f32_32x32x16_bf16 v[2:17], v[166:169], v[200:203], v[2:17]
	ds_read_b64_tr_b16 v[178:179], v199 offset:53248
	ds_read_b64_tr_b16 v[180:181], v199 offset:53760
	v_add_f32_e32 v187, v187, v114
	v_fmamk_f32 v84, v188, 0x42080000, v66
	v_fmamk_f32 v69, v188, 0x40400000, v66
	v_cvt_pk_bf16_f32 v158, v114, v115
	v_add_f32_e32 v187, v115, v187
	v_exp_f32_e32 v118, v118
	s_waitcnt lgkmcnt(2)
	v_mfma_f32_32x32x16_bf16 v[2:17], v[162:165], v[182:185], v[2:17]
	ds_read_b64_tr_b16 v[200:201], v199 offset:54272
	ds_read_b64_tr_b16 v[202:203], v199 offset:54784
	v_fma_f32 v85, v188, s16, v66
	v_fma_f32 v86, v188, s17, v66
	v_fmamk_f32 v70, v188, 0x41000000, v66
	v_exp_f32_e32 v119, v119
	v_add_f32_e32 v187, v187, v116
	s_waitcnt lgkmcnt(2)
	v_mfma_f32_32x32x16_bf16 v[18:33], v[174:177], v[178:181], v[18:33]
	ds_read_b64_tr_b16 v[182:183], v199 offset:55296
	ds_read_b64_tr_b16 v[184:185], v199 offset:55808
	v_fmamk_f32 v71, v188, 0x41100000, v66
	v_fmamk_f32 v87, v188, 0x42240000, v66
	v_cvt_pk_bf16_f32 v159, v116, v117
	v_add_f32_e32 v187, v187, v117
	v_exp_f32_e32 v120, v120
	s_waitcnt lgkmcnt(2)
	v_mfma_f32_32x32x16_bf16 v[18:33], v[170:173], v[200:203], v[18:33]
	ds_read_b64_tr_b16 v[178:179], v199 offset:56320
	ds_read_b64_tr_b16 v[180:181], v199 offset:56832
	v_fmamk_f32 v72, v188, 0x41200000, v66
	v_fmamk_f32 v88, v188, 0x42280000, v66
	v_exp_f32_e32 v121, v121
	v_add_f32_e32 v187, v187, v118
	v_cvt_pk_bf16_f32 v160, v118, v119
	s_waitcnt lgkmcnt(2)
	v_mfma_f32_32x32x16_bf16 v[18:33], v[166:169], v[182:185], v[18:33]
	ds_read_b64_tr_b16 v[200:201], v199 offset:57344
	ds_read_b64_tr_b16 v[202:203], v199 offset:57856
	v_fmamk_f32 v73, v188, 0x41300000, v66
	v_fmamk_f32 v89, v188, 0x422c0000, v66
	v_add_f32_e32 v182, v187, v119
	v_exp_f32_e32 v122, v122
	v_exp_f32_e32 v123, v123
	s_waitcnt lgkmcnt(2)
	v_mfma_f32_32x32x16_bf16 v[18:33], v[162:165], v[178:181], v[18:33]
	ds_read_b64_tr_b16 v[204:205], v199 offset:58368
	ds_read_b64_tr_b16 v[206:207], v199 offset:58880
	v_add_f32_e32 v178, v182, v120
	v_fmamk_f32 v90, v188, 0x42400000, v66
	v_fma_f32 v74, v188, s48, v66
	v_fma_f32 v75, v188, s49, v66
	v_cvt_pk_bf16_f32 v161, v120, v121
	v_add_f32_e32 v187, v121, v178
	s_waitcnt lgkmcnt(2)
	v_mfma_f32_32x32x16_bf16 v[34:49], v[174:177], v[200:203], v[34:49]
	ds_read_b64_tr_b16 v[182:183], v199 offset:59392
	ds_read_b64_tr_b16 v[184:185], v199 offset:59904
	v_fmamk_f32 v91, v188, 0x42440000, v66
	v_fmamk_f32 v76, v188, 0x41900000, v66
	v_exp_f32_e32 v124, v124
	v_exp_f32_e32 v125, v125
	s_waitcnt lgkmcnt(2)
	v_mfma_f32_32x32x16_bf16 v[34:49], v[170:173], v[204:207], v[34:49]
	ds_read_b64_tr_b16 v[178:179], v199 offset:60416
	ds_read_b64_tr_b16 v[180:181], v199 offset:60928
	v_add_f32_e32 v187, v187, v122
	v_fmamk_f32 v92, v188, 0x42480000, v66
	v_fmamk_f32 v77, v188, 0x41980000, v66
	v_cvt_pk_bf16_f32 v154, v122, v123
	v_add_f32_e32 v198, v123, v187
	v_exp_f32_e32 v126, v126
	s_add_u32 s6, s76, s62
	s_addc_u32 s7, s77, s63
	s_add_u32 s6, s6, 0x40000
	s_addc_u32 s7, s7, 0
	s_add_u32 s15, s78, s62
	s_addc_u32 s20, s79, s63
	s_add_u32 s24, s15, 0x40000
	s_addc_u32 s25, s20, 0
	s_add_i32 s15, 0x8000, s59
	s_add_i32 s20, s21, s90
	s_add_u32 s26, s6, 0x8000
	s_addc_u32 s27, s7, 0
	s_add_i32 s68, s15, 0x2000
	s_mov_b32 m0, s15
	s_nop 0
	global_load_lds_dwordx4 v191, s[6:7]
	s_mov_b32 m0, s68
	s_nop 0
	global_load_lds_dwordx4 v191, s[26:27]
	s_mov_b32 m0, s69
	s_add_u32 s6, s24, 0x80
	s_addc_u32 s7, s25, 0
	s_add_i32 s15, s20, 0x2000
	s_mov_b32 m0, s20
	s_nop 0
	global_load_lds_dwordx4 v192, s[24:25]
	s_mov_b32 m0, s15
	s_nop 0
	global_load_lds_dwordx4 v192, s[6:7]
	s_mov_b32 m0, s26
	s_waitcnt lgkmcnt(2)
	v_mfma_f32_32x32x16_bf16 v[34:49], v[166:169], v[182:185], v[34:49]
	ds_read_b64_tr_b16 v[200:201], v199 offset:61440
	ds_read_b64_tr_b16 v[202:203], v199 offset:61952
	s_add_i32 s6, s80, 0x4000
	s_cmp_lg_u32 s80, 0x10000
	v_fma_f32 v93, v188, s56, v66
	v_fma_f32 v94, v188, s57, v66
	s_cselect_b32 s15, s6, 0
	v_fmamk_f32 v78, v188, 0x41c00000, v66
	v_exp_f32_e32 v127, v127
	v_add_f32_e32 v187, v198, v124
	s_waitcnt lgkmcnt(2)
	v_mfma_f32_32x32x16_bf16 v[34:49], v[162:165], v[178:181], v[34:49]
	ds_read_b64_tr_b16 v[182:183], v199 offset:62464
	ds_read_b64_tr_b16 v[184:185], v199 offset:62976
	v_fmamk_f32 v79, v188, 0x41c80000, v66
	v_fmamk_f32 v95, v188, 0x42640000, v66
	v_cvt_pk_bf16_f32 v155, v124, v125
	v_add_f32_e32 v187, v187, v125
	v_exp_f32_e32 v128, v128
	s_waitcnt lgkmcnt(2)
	v_mfma_f32_32x32x16_bf16 v[50:65], v[174:177], v[200:203], v[50:65]
	ds_read_b64_tr_b16 v[178:179], v199 offset:63488
	ds_read_b64_tr_b16 v[180:181], v199 offset:64000
	v_fmamk_f32 v80, v188, 0x41d00000, v66
	v_fmamk_f32 v96, v188, 0x42680000, v66
	v_exp_f32_e32 v129, v129
	v_add_f32_e32 v187, v187, v126
	v_cvt_pk_bf16_f32 v156, v126, v127
	s_waitcnt lgkmcnt(2)
	v_mfma_f32_32x32x16_bf16 v[50:65], v[170:173], v[182:185], v[50:65]
	ds_read_b64_tr_b16 v[200:201], v199 offset:64512
	ds_read_b64_tr_b16 v[202:203], v199 offset:65024
	v_fmamk_f32 v81, v188, 0x41d80000, v66
	v_fmamk_f32 v97, v188, 0x426c0000, v66
	v_exp_f32_e32 v98, v98
	v_exp_f32_e32 v99, v99
	v_add_f32_e32 v186, v187, v127
	s_waitcnt lgkmcnt(2)
	v_mfma_f32_32x32x16_bf16 v[50:65], v[166:169], v[178:181], v[50:65]
	ds_read_b128 v[182:185], v190
	v_add_f32_e32 v178, v186, v128
	v_cvt_pk_bf16_f32 v157, v128, v129
	v_add_f32_e32 v186, v129, v178
	v_exp_f32_e32 v100, v100
	v_exp_f32_e32 v101, v101
	s_waitcnt lgkmcnt(1)
	v_mfma_f32_32x32x16_bf16 v[50:65], v[162:165], v[200:203], v[50:65]
	ds_read_b128 v[178:181], v190 offset:8192
	v_add_f32_e32 v186, v186, v98
	v_cvt_pk_bf16_f32 v150, v98, v99
	v_add_f32_e32 v198, v99, v186
	v_exp_f32_e32 v102, v102
	v_exp_f32_e32 v103, v103
	s_waitcnt lgkmcnt(1)
	v_mfma_f32_32x32x16_bf16 v[66:81], v[182:185], v[130:133], v[66:81]
	ds_read_b128 v[186:189], v194
	v_add_f32_e32 v182, v198, v100
	v_cvt_pk_bf16_f32 v151, v100, v101
	v_add_f32_e32 v198, v101, v182
	v_exp_f32_e32 v104, v104
	v_exp_f32_e32 v105, v105
	s_waitcnt lgkmcnt(1)
	v_mfma_f32_32x32x16_bf16 v[82:97], v[178:181], v[130:133], v[82:97]
	ds_read_b128 v[182:185], v194 offset:8192
	v_add_f32_e32 v178, v198, v102
	v_cvt_pk_bf16_f32 v152, v102, v103
	v_add_f32_e32 v198, v103, v178
	v_exp_f32_e32 v106, v106
	v_exp_f32_e32 v107, v107
	s_waitcnt lgkmcnt(1)
	v_mfma_f32_32x32x16_bf16 v[66:81], v[186:189], v[134:137], v[66:81]
	ds_read_b128 v[178:181], v195
	v_add_f32_e32 v186, v198, v104
	v_cvt_pk_bf16_f32 v153, v104, v105
	v_add_f32_e32 v198, v105, v186
	v_exp_f32_e32 v108, v108
	v_exp_f32_e32 v109, v109
	s_waitcnt lgkmcnt(1)
	v_mfma_f32_32x32x16_bf16 v[82:97], v[182:185], v[134:137], v[82:97]
	ds_read_b128 v[186:189], v195 offset:8192
	v_add_f32_e32 v182, v198, v106
	v_cvt_pk_bf16_f32 v146, v106, v107
	v_add_f32_e32 v182, v107, v182
	v_exp_f32_e32 v110, v110
	v_exp_f32_e32 v111, v111
	s_waitcnt lgkmcnt(1)
	v_mfma_f32_32x32x16_bf16 v[66:81], v[178:181], v[138:141], v[66:81]
	ds_read_b128 v[198:201], v196
	v_add_f32_e32 v178, v182, v108
	v_cvt_pk_bf16_f32 v147, v108, v109
	v_add_f32_e32 v178, v109, v178
	v_exp_f32_e32 v112, v112
	v_exp_f32_e32 v113, v113
	s_waitcnt lgkmcnt(1)
	v_mfma_f32_32x32x16_bf16 v[82:97], v[186:189], v[138:141], v[82:97]
	ds_read_b128 v[202:205], v196 offset:8192
	v_add_f32_e32 v149, v178, v110
	v_add_f32_e32 v149, v111, v149
	v_add_f32_e32 v178, v112, v149
	v_cvt_pk_bf16_f32 v148, v110, v111
	v_cvt_pk_bf16_f32 v149, v112, v113
	v_add_f32_e32 v187, v113, v178
	s_waitcnt lgkmcnt(1)
	v_mfma_f32_32x32x16_bf16 v[66:81], v[198:201], v[142:145], v[66:81]
	v_add_u32_e32 v180, s15, v240
	ds_read_b64_tr_b16 v[182:183], v180 offset:49152
	ds_read_b64_tr_b16 v[184:185], v180 offset:49664
	s_waitcnt lgkmcnt(2)
	v_mfma_f32_32x32x16_bf16 v[82:97], v[202:205], v[142:145], v[82:97]
	ds_read_b64_tr_b16 v[178:179], v180 offset:50176
	ds_read_b64_tr_b16 v[180:181], v180 offset:50688
	s_add_i32 s6, s15, 0x4000
	s_cmp_lg_u32 s15, 0x10000
	s_cselect_b32 s80, s6, 0
	s_add_i32 s6, s21, 0x4000
	s_cmp_lg_u32 s21, 0x10000
	s_cselect_b32 s81, s6, 0
	s_add_u32 s78, s78, 0x20000
	s_addc_u32 s79, s79, 0
	s_add_u32 s76, s76, 0x20000
	s_addc_u32 s77, s77, 0
	v_add_u32_e32 v197, 0x80, v197
	s_mov_b32 s43, s0
	s_branch .LBB0_1377
